# both rms-norm row loops: the 6-step wave sum done with DPP / permlane swaps instead of six ds_bpermute round trips (same add order), on top of v42
# baseline (speedup 1.0000x reference)
.LBB0_191:
	s_waitcnt vmcnt(3)
	v_mul_f32_e32 v0, v31, v31
	s_waitcnt vmcnt(2)
	v_mul_f32_e32 v42, v27, v27
	v_fmac_f32_e32 v0, v30, v30
	v_fmac_f32_e32 v42, v26, v26
	v_fmac_f32_e32 v0, v32, v32
	v_fmac_f32_e32 v42, v28, v28
	v_fmac_f32_e32 v0, v33, v33
	v_fmac_f32_e32 v42, v29, v29
	s_waitcnt vmcnt(0)
	v_pk_mul_f32 v[46:47], v[18:19], v[18:19]
	v_pk_mul_f32 v[58:59], v[22:23], v[22:23]
	v_add_f32_e32 v0, v0, v42
	v_pk_mul_f32 v[42:43], v[20:21], v[20:21]
	v_pk_mul_f32 v[44:45], v[24:25], v[24:25]
	v_mov_b32_e32 v60, v46
	v_mov_b32_e32 v61, v58
	v_mov_b32_e32 v58, v47
	v_pk_add_f32 v[46:47], v[60:61], v[58:59]
	v_mov_b32_e32 v58, v42
	v_mov_b32_e32 v59, v44
	v_pk_add_f32 v[46:47], v[58:59], v[46:47]
	v_mov_b32_e32 v44, v43
	v_pk_add_f32 v[42:43], v[44:45], v[46:47]
	s_cmpk_lt_u32 s2, 0x4000
	v_add_f32_e32 v0, v43, v0
	v_add_f32_e32 v0, v42, v0
	s_nop 1
	v_add_f32_dpp v0, v0, v0 quad_perm:[1,0,3,2] row_mask:0xf bank_mask:0xf
	s_movk_i32 s0, 0x4800
	s_cselect_b32 s0, 0x2400, s0
	s_cmpk_gt_i32 s2, 0x1fff
	s_cselect_b32 s0, s0, 0
	s_nop 1
	v_add_f32_dpp v0, v0, v0 quad_perm:[2,3,0,1] row_mask:0xf bank_mask:0xf
	s_lshl_b32 s0, s0, 2
	v_readlane_b32 s1, v254, 45
	s_add_u32 s0, s1, s0
	v_readlane_b32 s1, v254, 47
	s_nop 1
	v_add_f32_dpp v0, v0, v0 row_half_mirror row_mask:0xf bank_mask:0xf
	s_addc_u32 s1, s1, 0
	s_add_u32 s4, s0, 0x3000
	s_addc_u32 s5, s1, 0
	s_add_u32 s6, s0, 0x4000
	s_nop 1
	v_add_f32_dpp v0, v0, v0 row_mirror row_mask:0xf bank_mask:0xf
	s_addc_u32 s7, s1, 0
	global_load_dwordx4 v[100:103], v56, s[6:7]
	global_load_dwordx4 v[104:107], v56, s[4:5]
	global_load_dwordx4 v[108:111], v53, s[6:7]
	global_load_dwordx4 v[112:115], v53, s[4:5]
	global_load_dwordx4 v[116:119], v54, s[6:7]
	global_load_dwordx4 v[120:123], v54, s[4:5]
	global_load_dwordx4 v[124:127], v55, s[6:7]
	global_load_dwordx4 v[128:131], v55, s[4:5]
	v_mov_b32_e32 v42, v0
	s_nop 1
	v_permlane16_swap_b32_e32 v42, v0
	s_nop 1
	v_add_f32_e32 v0, v0, v42
	v_mov_b32_e32 v42, v0
	s_nop 1
	v_permlane32_swap_b32_e32 v42, v0
	s_nop 1
	v_add_f32_e32 v0, v0, v42
	v_fmamk_f32 v0, v0, 0x3a800000, v199
	v_cmp_gt_f32_e32 vcc, s21, v0
	v_mul_f32_e32 v42, 0x4f800000, v0
	s_nop 0
	v_cndmask_b32_e32 v0, v0, v42, vcc
	v_sqrt_f32_e32 v42, v0
	s_nop 0
	v_add_u32_e32 v43, -1, v42
	v_fma_f32 v44, -v43, v42, v0
	v_cmp_ge_f32_e64 s[38:39], 0, v44
	v_add_u32_e32 v44, 1, v42
	s_nop 0
	v_cndmask_b32_e64 v43, v42, v43, s[38:39]
	v_fma_f32 v42, -v44, v42, v0
	v_cmp_lt_f32_e64 s[38:39], 0, v42
	s_nop 1
	v_cndmask_b32_e64 v42, v43, v44, s[38:39]
	v_mul_f32_e32 v43, 0x37800000, v42
	v_cndmask_b32_e32 v42, v42, v43, vcc
	v_cmp_class_f32_e32 vcc, v0, v200
	s_nop 1
	v_cndmask_b32_e32 v0, v42, v0, vcc
	v_div_scale_f32 v42, s[0:1], v0, v0, 1.0
	v_rcp_f32_e32 v43, v42
	v_readlane_b32 s0, v249, 52
	v_readlane_b32 s1, v249, 53
	s_add_u32 s2, s2, s0
	v_fma_f32 v44, -v42, v43, 1.0
	v_fmac_f32_e32 v43, v44, v43
	v_div_scale_f32 v44, vcc, 1.0, v0, 1.0
	v_mul_f32_e32 v45, v44, v43
	v_fma_f32 v46, -v42, v45, v44
	v_fmac_f32_e32 v45, v46, v43
	v_fma_f32 v42, -v42, v45, v44
	v_div_fmas_f32 v42, v42, v43, v45
	v_div_fixup_f32 v0, v42, v0, 1.0
	v_pk_mul_f32 v[30:31], v[30:31], v[0:1] op_sel_hi:[1,0]
	v_pk_mul_f32 v[32:33], v[32:33], v[0:1] op_sel_hi:[1,0]
	v_pk_mul_f32 v[30:31], v[2:3], v[30:31]
	v_pk_mul_f32 v[32:33], v[4:5], v[32:33]
	v_pk_mul_f32 v[26:27], v[26:27], v[0:1] op_sel_hi:[1,0]
	v_pk_mul_f32 v[28:29], v[28:29], v[0:1] op_sel_hi:[1,0]
	v_pk_mul_f32 v[26:27], v[6:7], v[26:27]
	v_pk_mul_f32 v[28:29], v[8:9], v[28:29]
	v_pk_mul_f32 v[22:23], v[22:23], v[0:1] op_sel_hi:[1,0]
	v_pk_mul_f32 v[24:25], v[24:25], v[0:1] op_sel_hi:[1,0]
	v_pk_mul_f32 v[22:23], v[10:11], v[22:23]
	v_pk_mul_f32 v[24:25], v[12:13], v[24:25]
	v_pk_mul_f32 v[18:19], v[18:19], v[0:1] op_sel_hi:[1,0]
	v_pk_mul_f32 v[20:21], v[20:21], v[0:1] op_sel_hi:[1,0]
	v_pk_mul_f32 v[18:19], v[18:19], v[14:15]
	v_pk_mul_f32 v[20:21], v[20:21], v[16:17]
	s_addc_u32 s3, s3, s1
	v_readlane_b32 s0, v253, 22
	v_readlane_b32 s1, v253, 23
	s_cmpk_gt_i32 s2, 0x41ff
	s_waitcnt vmcnt(0)
	v_pk_add_f32 v[42:43], v[100:101], 1.0 op_sel_hi:[1,0]
	s_nop 0
	v_pk_fma_f32 v[30:31], v[42:43], v[30:31], v[104:105]
	v_pk_add_f32 v[42:43], v[102:103], 1.0 op_sel_hi:[1,0]
	v_cvt_pk_bf16_f32 v30, v30, v31
	v_pk_fma_f32 v[32:33], v[42:43], v[32:33], v[106:107]
	s_nop 0
	v_cvt_pk_bf16_f32 v31, v32, v33
	global_store_dwordx2 v[40:41], v[30:31], off
	v_pk_add_f32 v[30:31], v[108:109], 1.0 op_sel_hi:[1,0]
	s_nop 0
	v_pk_fma_f32 v[26:27], v[30:31], v[26:27], v[112:113]
	v_pk_add_f32 v[30:31], v[110:111], 1.0 op_sel_hi:[1,0]
	v_cvt_pk_bf16_f32 v26, v26, v27
	v_pk_fma_f32 v[28:29], v[30:31], v[28:29], v[114:115]
	s_nop 0
	v_cvt_pk_bf16_f32 v27, v28, v29
	global_store_dwordx2 v[40:41], v[26:27], off offset:512
	v_pk_add_f32 v[26:27], v[116:117], 1.0 op_sel_hi:[1,0]
	s_nop 0
	v_pk_fma_f32 v[22:23], v[22:23], v[26:27], v[120:121]
	v_pk_add_f32 v[26:27], v[118:119], 1.0 op_sel_hi:[1,0]
	v_cvt_pk_bf16_f32 v22, v22, v23
	v_pk_fma_f32 v[24:25], v[24:25], v[26:27], v[122:123]
	s_nop 0
	v_cvt_pk_bf16_f32 v23, v24, v25
	global_store_dwordx2 v[40:41], v[22:23], off offset:1024
	v_pk_add_f32 v[26:27], v[124:125], 1.0 op_sel_hi:[1,0]
	s_nop 0
	v_pk_fma_f32 v[18:19], v[18:19], v[26:27], v[128:129]
	v_pk_add_f32 v[22:23], v[126:127], 1.0 op_sel_hi:[1,0]
	v_cvt_pk_bf16_f32 v18, v18, v19
	v_pk_fma_f32 v[20:21], v[20:21], v[22:23], v[130:131]
	s_nop 0
	v_cvt_pk_bf16_f32 v19, v20, v21
	global_store_dwordx2 v[40:41], v[18:19], off offset:1536
	v_lshl_add_u64 v[40:41], v[40:41], 0, s[0:1]
	s_cbranch_scc1 .LBB0_194

.LBB0_1101:
	s_waitcnt vmcnt(3)
	v_mul_f32_e32 v0, v31, v31
	s_waitcnt vmcnt(2)
	v_mul_f32_e32 v40, v27, v27
	v_fmac_f32_e32 v0, v30, v30
	v_fmac_f32_e32 v40, v26, v26
	v_fmac_f32_e32 v0, v32, v32
	v_fmac_f32_e32 v40, v28, v28
	v_fmac_f32_e32 v0, v33, v33
	v_fmac_f32_e32 v40, v29, v29
	s_waitcnt vmcnt(0)
	v_pk_mul_f32 v[54:55], v[18:19], v[18:19]
	v_pk_mul_f32 v[56:57], v[22:23], v[22:23]
	v_add_f32_e32 v0, v0, v40
	v_pk_mul_f32 v[40:41], v[20:21], v[20:21]
	v_pk_mul_f32 v[52:53], v[24:25], v[24:25]
	v_mov_b32_e32 v58, v54
	v_mov_b32_e32 v59, v56
	v_mov_b32_e32 v56, v55
	v_pk_add_f32 v[54:55], v[58:59], v[56:57]
	v_mov_b32_e32 v56, v40
	v_mov_b32_e32 v57, v52
	v_pk_add_f32 v[54:55], v[56:57], v[54:55]
	v_mov_b32_e32 v52, v41
	v_pk_add_f32 v[40:41], v[52:53], v[54:55]
	s_cmpk_lt_u32 s6, 0x4000
	v_add_f32_e32 v0, v41, v0
	v_add_f32_e32 v0, v40, v0
	s_nop 1
	v_add_f32_dpp v0, v0, v0 quad_perm:[1,0,3,2] row_mask:0xf bank_mask:0xf
	s_movk_i32 s5, 0x4800
	s_cselect_b32 s5, 0x2400, s5
	s_cmpk_gt_i32 s6, 0x1fff
	s_cselect_b32 s5, s5, 0
	s_nop 1
	v_add_f32_dpp v0, v0, v0 quad_perm:[2,3,0,1] row_mask:0xf bank_mask:0xf
	s_lshl_b32 s5, s5, 2
	s_add_u32 s8, s0, s5
	s_addc_u32 s9, s1, 0
	s_add_u32 s10, s8, 0x1000
	s_nop 1
	v_add_f32_dpp v0, v0, v0 row_half_mirror row_mask:0xf bank_mask:0xf
	s_addc_u32 s11, s9, 0
	global_load_dwordx4 v[60:63], v48, s[10:11]
	global_load_dwordx4 v[64:67], v48, s[8:9]
	global_load_dwordx4 v[68:71], v49, s[10:11]
	global_load_dwordx4 v[72:75], v48, s[8:9] offset:1024
	global_load_dwordx4 v[76:79], v50, s[10:11]
	global_load_dwordx4 v[80:83], v48, s[8:9] offset:2048
	global_load_dwordx4 v[84:87], v51, s[10:11]
	global_load_dwordx4 v[88:91], v48, s[8:9] offset:3072
	v_readlane_b32 s36, v249, 52
	s_add_i32 s36, s6, s36
	s_cmp_ge_i32 s36, s12
	s_cbranch_scc1 .Lnf_selftouch
	s_add_i32 s37, s36, 0xffffc000
	s_cmpk_lt_i32 s36, 0x4000
	s_cselect_b32 s38, s36, s37
	s_cselect_b32 s27, s79, s97
	s_cselect_b32 s26, s78, s96
	s_ashr_i32 s39, s38, 31
	s_lshl_b64 s[38:39], s[38:39], 12
	s_add_u32 s26, s26, s38
	s_addc_u32 s27, s27, s39
	s_branch .Lnf_touch

.Lnf_touch:
	global_load_dwordx4 v[92:95], v48, s[26:27]
	global_load_dwordx4 v[92:95], v48, s[26:27] offset:1024
	global_load_dwordx4 v[92:95], v48, s[26:27] offset:2048
	global_load_dwordx4 v[92:95], v48, s[26:27] offset:3072
	s_nop 1
	v_add_f32_dpp v0, v0, v0 row_mirror row_mask:0xf bank_mask:0xf
	v_mov_b32_e32 v40, v0
	s_nop 1
	v_permlane16_swap_b32_e32 v40, v0
	s_nop 1
	v_add_f32_e32 v0, v0, v40
	v_mov_b32_e32 v40, v0
	s_nop 1
	v_permlane32_swap_b32_e32 v40, v0
	s_nop 1
	v_add_f32_e32 v0, v0, v40
	v_fmamk_f32 v0, v0, 0x3a800000, v199
	v_cmp_gt_f32_e32 vcc, s21, v0
	v_mul_f32_e32 v40, 0x4f800000, v0
	s_nop 0
	v_cndmask_b32_e32 v0, v0, v40, vcc
	v_sqrt_f32_e32 v40, v0
	s_nop 0
	v_add_u32_e32 v41, -1, v40
	v_fma_f32 v52, -v41, v40, v0
	v_cmp_ge_f32_e64 s[38:39], 0, v52
	v_add_u32_e32 v52, 1, v40
	s_nop 0
	v_cndmask_b32_e64 v41, v40, v41, s[38:39]
	v_fma_f32 v40, -v52, v40, v0
	v_cmp_lt_f32_e64 s[38:39], 0, v40
	s_nop 1
	v_cndmask_b32_e64 v40, v41, v52, s[38:39]
	v_mul_f32_e32 v41, 0x37800000, v40
	v_cndmask_b32_e32 v40, v40, v41, vcc
	v_cmp_class_f32_e32 vcc, v0, v200
	s_nop 1
	v_cndmask_b32_e32 v0, v40, v0, vcc
	v_div_scale_f32 v40, s[16:17], v0, v0, 1.0
	v_rcp_f32_e32 v41, v40
	s_lshl_b64 s[16:17], s[6:7], 11
	v_fma_f32 v52, -v40, v41, 1.0
	v_fmac_f32_e32 v41, v52, v41
	v_div_scale_f32 v52, vcc, 1.0, v0, 1.0
	v_mul_f32_e32 v53, v52, v41
	v_fma_f32 v54, -v40, v53, v52
	v_fmac_f32_e32 v53, v54, v41
	v_fma_f32 v40, -v40, v53, v52
	v_div_fmas_f32 v40, v40, v41, v53
	v_div_fixup_f32 v0, v40, v0, 1.0
	v_pk_mul_f32 v[30:31], v[30:31], v[0:1] op_sel_hi:[1,0]
	v_pk_mul_f32 v[32:33], v[32:33], v[0:1] op_sel_hi:[1,0]
	v_pk_mul_f32 v[30:31], v[2:3], v[30:31]
	v_pk_mul_f32 v[32:33], v[4:5], v[32:33]
	v_pk_mul_f32 v[26:27], v[26:27], v[0:1] op_sel_hi:[1,0]
	v_pk_mul_f32 v[28:29], v[28:29], v[0:1] op_sel_hi:[1,0]
	v_pk_mul_f32 v[26:27], v[6:7], v[26:27]
	v_pk_mul_f32 v[28:29], v[8:9], v[28:29]
	v_pk_mul_f32 v[22:23], v[22:23], v[0:1] op_sel_hi:[1,0]
	v_pk_mul_f32 v[24:25], v[24:25], v[0:1] op_sel_hi:[1,0]
	v_pk_mul_f32 v[22:23], v[10:11], v[22:23]
	v_pk_mul_f32 v[24:25], v[12:13], v[24:25]
	v_pk_mul_f32 v[18:19], v[18:19], v[0:1] op_sel_hi:[1,0]
	v_pk_mul_f32 v[20:21], v[20:21], v[0:1] op_sel_hi:[1,0]
	v_pk_mul_f32 v[18:19], v[18:19], v[14:15]
	v_pk_mul_f32 v[20:21], v[20:21], v[16:17]
	s_waitcnt vmcnt(4)
	v_pk_add_f32 v[40:41], v[60:61], 1.0 op_sel_hi:[1,0]
	s_nop 0
	v_pk_fma_f32 v[30:31], v[40:41], v[30:31], v[64:65]
	v_pk_add_f32 v[40:41], v[62:63], 1.0 op_sel_hi:[1,0]
	s_nop 0
	v_pk_fma_f32 v[32:33], v[40:41], v[32:33], v[66:67]
	v_cvt_pk_bf16_f32 v40, v30, v31
	v_cvt_pk_bf16_f32 v41, v32, v33
	v_lshl_add_u64 v[30:31], v[36:37], 0, s[16:17]
	global_store_dwordx2 v[30:31], v[40:41], off
	v_pk_add_f32 v[32:33], v[68:69], 1.0 op_sel_hi:[1,0]
	s_nop 0
	v_pk_fma_f32 v[26:27], v[32:33], v[26:27], v[72:73]
	v_pk_add_f32 v[32:33], v[70:71], 1.0 op_sel_hi:[1,0]
	v_cvt_pk_bf16_f32 v26, v26, v27
	v_pk_fma_f32 v[28:29], v[32:33], v[28:29], v[74:75]
	s_nop 0
	v_cvt_pk_bf16_f32 v27, v28, v29
	global_store_dwordx2 v[30:31], v[26:27], off offset:512
	v_pk_add_f32 v[26:27], v[76:77], 1.0 op_sel_hi:[1,0]
	s_nop 0
	v_pk_fma_f32 v[22:23], v[22:23], v[26:27], v[80:81]
	v_pk_add_f32 v[26:27], v[78:79], 1.0 op_sel_hi:[1,0]
	v_cvt_pk_bf16_f32 v22, v22, v23
	v_pk_fma_f32 v[24:25], v[24:25], v[26:27], v[82:83]
	s_nop 0
	v_cvt_pk_bf16_f32 v23, v24, v25
	global_store_dwordx2 v[30:31], v[22:23], off offset:1024
	v_readlane_b32 s8, v249, 52
	s_add_i32 s6, s6, s8
	s_add_i32 s4, s4, s8
	s_cmp_ge_i32 s6, s12
	v_readlane_b32 s9, v249, 53
	v_pk_add_f32 v[26:27], v[84:85], 1.0 op_sel_hi:[1,0]
	s_nop 0
	v_pk_fma_f32 v[18:19], v[18:19], v[26:27], v[88:89]
	v_pk_add_f32 v[22:23], v[86:87], 1.0 op_sel_hi:[1,0]
	v_cvt_pk_bf16_f32 v18, v18, v19
	v_pk_fma_f32 v[20:21], v[20:21], v[22:23], v[90:91]
	s_nop 0
	v_cvt_pk_bf16_f32 v19, v20, v21
	global_store_dwordx2 v[30:31], v[18:19], off offset:1536
	s_cbranch_scc1 .LBB0_1106
